# v18
# baseline (speedup 1.0000x reference)
; __device__ __forceinline__ void finishSM(f32x16& p0, f32x16& p1, float alpha, float& l_reg, bf16x8& pa0, bf16x8& pa1, bf16x8& pa2, bf16x8& pa3) {
; #pragma unroll
;   for (int r = 0; r < 16; ++r) p1[r] = __builtin_amdgcn_exp2f(p1[r]);
;   float ps = 0;
; #pragma unroll
;   for (int r = 0; r < 16; ++r) ps += p0[r];
; #pragma unroll
;   for (int r = 0; r < 16; ++r) ps += p1[r];
;   { auto rr = __builtin_amdgcn_permlane32_swap(__float_as_uint(ps), __float_as_uint(ps), false, false);
;     ps = __uint_as_float(rr[0]) + __uint_as_float(rr[1]); }
;   l_reg = l_reg * alpha + ps;
;     ...
;   PK4(p0, 0, pa0); PK4(p0, 8, pa1); PK4(p1, 0, pa2); PK4(p1, 8, pa3);
;     ...
; }
; __device__ __forceinline__ void qkt(f32x16& p0, f32x16& p1, const char* Ks, const char* Krs, const bf16x8* qr, const char* Qrs, int r32, int hi) {
;   p0 = f32x16{}; p1 = f32x16{};
; #pragma unroll
;   for (int d0 = 0; d0 < 8; ++d0) { const int cb = (d0 * 16 + hi * 8) * 2;
;     const bf16x8 b0 = *reinterpret_cast<const bf16x8*>(Ks + KSWZ(r32, cb));
;     const bf16x8 b1 = *reinterpret_cast<const bf16x8*>(Ks + KSWZ(32 + r32, cb));
;     p0 = __builtin_amdgcn_mfma_f32_32x32x16_bf16(b0, qr[d0], p0, 0, 0, 0);
;     p1 = __builtin_amdgcn_mfma_f32_32x32x16_bf16(b1, qr[d0], p1, 0, 0, 0); }
; #pragma unroll
;   for (int d0 = 0; d0 < 4; ++d0) { const int slot = d0 * 2 + hi;
;     const bf16x8 b0 = *reinterpret_cast<const bf16x8*>(Krs + RSWZ(r32, slot));
;     const bf16x8 b1 = *reinterpret_cast<const bf16x8*>(Krs + RSWZ(32 + r32, slot));
;     const bf16x8 qf = *reinterpret_cast<const bf16x8*>(Qrs + RSWZ(r32, slot));
;     p0 = __builtin_amdgcn_mfma_f32_32x32x16_bf16(b0, qf, p0, 0, 0, 0);
;     p1 = __builtin_amdgcn_mfma_f32_32x32x16_bf16(b1, qf, p1, 0, 0, 0); }
; }
.LBB0_357:
	s_waitcnt vmcnt(0)
	s_waitcnt lgkmcnt(0)
	s_barrier
	s_add_u32 s46, s70, 0x20000
	s_addc_u32 s47, s71, 0
	ds_read_b128 v[64:67], v169 offset:32768
	ds_read_b128 v[68:71], v169 offset:40960
	ds_read_b128 v[224:227], v170 offset:32768
	ds_read_b128 v[228:231], v170 offset:40960
	ds_read_b128 v[240:243], v171 offset:32768
	ds_read_b128 v[244:247], v171 offset:40960
	v_exp_f32_e32 v159, v210
	v_add_f32_e32 v210, 0, v143
	s_add_u32 m0, s98, 0xc000
	s_waitcnt lgkmcnt(5)
	v_mfma_f32_32x32x16_bf16 v[80:95], v[64:67], v[124:127], 0
	global_load_lds_dwordx4 v130, s[70:71]
	v_add_f32_e32 v210, v144, v210
	v_add_f32_e32 v210, v145, v210
	v_add_f32_e32 v210, v147, v210
	v_add_f32_e32 v210, v148, v210
	v_add_f32_e32 v210, v195, v210
	v_add_f32_e32 v210, v146, v210
	v_add_f32_e32 v210, v149, v210
	s_waitcnt lgkmcnt(4)
	v_mfma_f32_32x32x16_bf16 v[64:79], v[68:71], v[124:127], 0
	v_add_f32_e32 v210, v135, v210
	v_add_f32_e32 v210, v137, v210
	v_add_f32_e32 v210, v138, v210
	v_add_f32_e32 v210, v141, v210
	v_exp_f32_e32 v150, v217
	v_add_f32_e32 v210, v136, v210
	v_exp_f32_e32 v151, v218
	s_waitcnt lgkmcnt(3)
	v_mfma_f32_32x32x16_bf16 v[80:95], v[224:227], v[120:123], v[80:95]
	v_add_f32_e32 v210, v139, v210
	v_exp_f32_e32 v156, v219
	v_add_f32_e32 v210, v140, v210
	v_exp_f32_e32 v157, v220
	v_add_f32_e32 v210, v142, v210
	v_exp_f32_e32 v158, v221
	v_add_f32_e32 v210, v150, v210
	s_waitcnt lgkmcnt(2)
	v_mfma_f32_32x32x16_bf16 v[64:79], v[228:231], v[120:123], v[64:79]
	ds_read_b128 v[224:227], v172 offset:32768
	ds_read_b128 v[228:231], v172 offset:40960
	v_add_f32_e32 v210, v151, v210
	v_exp_f32_e32 v217, v211
	v_add_f32_e32 v210, v156, v210
	v_exp_f32_e32 v218, v212
	v_add_f32_e32 v210, v157, v210
	v_exp_f32_e32 v219, v213
	s_add_u32 m0, s98, 0xe000
	s_waitcnt lgkmcnt(3)
	v_mfma_f32_32x32x16_bf16 v[80:95], v[240:243], v[116:119], v[80:95]
	global_load_lds_dwordx4 v130, s[46:47]
	v_add_f32_e32 v210, v158, v210
	v_exp_f32_e32 v214, v214
	v_add_f32_e32 v210, v159, v210
	v_exp_f32_e32 v215, v215
	v_add_f32_e32 v210, v217, v210
	v_exp_f32_e32 v216, v216
	v_add_f32_e32 v210, v218, v210
	s_waitcnt lgkmcnt(2)
	v_mfma_f32_32x32x16_bf16 v[64:79], v[244:247], v[116:119], v[64:79]
	ds_read_b128 v[240:243], v173 offset:32768
	ds_read_b128 v[244:247], v173 offset:40960
	v_exp_f32_e32 v209, v209
	v_add_f32_e32 v210, v219, v210
	v_exp_f32_e32 v220, v222
	v_add_f32_e32 v210, v214, v210
	v_exp_f32_e32 v221, v223
	v_add_f32_e32 v210, v215, v210
	s_waitcnt lgkmcnt(3)
	v_mfma_f32_32x32x16_bf16 v[80:95], v[224:227], v[112:115], v[80:95]
	v_exp_f32_e32 v207, v207
	v_add_f32_e32 v210, v216, v210
	v_add_f32_e32 v210, v209, v210
	v_add_f32_e32 v210, v220, v210
	v_add_f32_e32 v210, v221, v210
	v_cvt_pk_bf16_f32 v211, v145, v147
	v_cvt_pk_bf16_f32 v212, v148, v195
	s_waitcnt lgkmcnt(2)
	v_mfma_f32_32x32x16_bf16 v[64:79], v[228:231], v[112:115], v[64:79]
	ds_read_b128 v[224:227], v174 offset:32768
	ds_read_b128 v[228:231], v174 offset:40960
	v_cvt_pk_bf16_f32 v213, v146, v149
	v_cvt_pk_bf16_f32 v145, v138, v141
	v_cvt_pk_bf16_f32 v146, v136, v139
	v_cvt_pk_bf16_f32 v147, v140, v142
	v_cvt_pk_bf16_f32 v136, v150, v151
	v_cvt_pk_bf16_f32 v138, v158, v159
	s_add_u32 m0, s98, 0x12000
	s_waitcnt lgkmcnt(3)
	v_mfma_f32_32x32x16_bf16 v[80:95], v[240:243], v[108:111], v[80:95]
	global_load_lds_dwordx4 v132, s[72:73]
	v_cvt_pk_bf16_f32 v139, v217, v218
	v_cvt_pk_bf16_f32 v140, v219, v214
	v_cvt_pk_bf16_f32 v141, v215, v216
	v_cvt_pk_bf16_f32 v142, v209, v220
	v_permlane32_swap_b32_e32 v211, v213
	v_permlane32_swap_b32_e32 v145, v147
	s_waitcnt lgkmcnt(2)
	v_mfma_f32_32x32x16_bf16 v[64:79], v[244:247], v[108:111], v[64:79]
	ds_read_b128 v[240:243], v175 offset:32768
	ds_read_b128 v[244:247], v175 offset:40960
	v_permlane32_swap_b32_e32 v136, v138
	v_permlane32_swap_b32_e32 v140, v142
	s_waitcnt lgkmcnt(3)
	v_mfma_f32_32x32x16_bf16 v[80:95], v[224:227], v[104:107], v[80:95]
	s_waitcnt lgkmcnt(2)
	v_mfma_f32_32x32x16_bf16 v[64:79], v[228:231], v[104:107], v[64:79]
	ds_read_b128 v[224:227], v176 offset:32768
	ds_read_b128 v[228:231], v176 offset:40960
	s_mov_b32 m0, s98
	s_waitcnt lgkmcnt(3)
	v_mfma_f32_32x32x16_bf16 v[80:95], v[240:243], v[100:103], v[80:95]
	global_load_lds_dwordx4 v131, s[70:71]
	s_waitcnt lgkmcnt(2)
	v_mfma_f32_32x32x16_bf16 v[64:79], v[244:247], v[100:103], v[64:79]
	ds_read_b128 v[240:243], v177
	ds_read_b128 v[244:247], v178
	ds_read_b128 v[248:251], v192
	s_waitcnt lgkmcnt(4)
	v_mfma_f32_32x32x16_bf16 v[80:95], v[224:227], v[96:99], v[80:95]
	s_waitcnt lgkmcnt(3)
	v_mfma_f32_32x32x16_bf16 v[64:79], v[228:231], v[96:99], v[64:79]
	ds_read_b128 v[224:227], v179
	ds_read_b128 v[228:231], v180
	ds_read_b128 v[232:235], v191
	s_add_u32 m0, s98, 0x2000
	s_waitcnt lgkmcnt(3)
	v_mfma_f32_32x32x16_bf16 v[80:95], v[240:243], v[248:251], v[80:95]
	global_load_lds_dwordx4 v131, s[46:47]
	s_add_u32 s70, s70, 0x40000
	s_addc_u32 s71, s71, 0
	s_add_u32 s72, s72, 0x2000
	s_addc_u32 s73, s73, 0
	s_waitcnt lgkmcnt(3)
	v_mfma_f32_32x32x16_bf16 v[64:79], v[244:247], v[248:251], v[64:79]
	ds_read_b128 v[240:243], v182
	ds_read_b128 v[244:247], v183
	ds_read_b128 v[248:251], v168
	s_waitcnt lgkmcnt(3)
	v_mfma_f32_32x32x16_bf16 v[80:95], v[224:227], v[232:235], v[80:95]
	s_waitcnt lgkmcnt(3)
	v_mfma_f32_32x32x16_bf16 v[64:79], v[228:231], v[232:235], v[64:79]
	ds_read_b128 v[224:227], v185
	ds_read_b128 v[228:231], v186
	ds_read_b128 v[232:235], v187
	s_waitcnt lgkmcnt(3)
	v_mfma_f32_32x32x16_bf16 v[80:95], v[240:243], v[248:251], v[80:95]
	s_waitcnt lgkmcnt(3)
	v_mfma_f32_32x32x16_bf16 v[64:79], v[244:247], v[248:251], v[64:79]
	s_waitcnt lgkmcnt(0)
; __device__ __forceinline__ void qkt(f32x16& p0, f32x16& p1, const char* Ks, const char* Krs, const bf16x8* qr, const char* Qrs, int r32, int hi) {
;   p0 = f32x16{}; p1 = f32x16{};
; #pragma unroll
;   for (int d0 = 0; d0 < 8; ++d0) { const int cb = (d0 * 16 + hi * 8) * 2;
;     const bf16x8 b0 = *reinterpret_cast<const bf16x8*>(Ks + KSWZ(r32, cb));
;     const bf16x8 b1 = *reinterpret_cast<const bf16x8*>(Ks + KSWZ(32 + r32, cb));
;     p0 = __builtin_amdgcn_mfma_f32_32x32x16_bf16(b0, qr[d0], p0, 0, 0, 0);
;     p1 = __builtin_amdgcn_mfma_f32_32x32x16_bf16(b1, qr[d0], p1, 0, 0, 0); }
; #pragma unroll
;   for (int d0 = 0; d0 < 4; ++d0) { const int slot = d0 * 2 + hi;
;     const bf16x8 b0 = *reinterpret_cast<const bf16x8*>(Krs + RSWZ(r32, slot));
;     const bf16x8 b1 = *reinterpret_cast<const bf16x8*>(Krs + RSWZ(32 + r32, slot));
;     const bf16x8 qf = *reinterpret_cast<const bf16x8*>(Qrs + RSWZ(r32, slot));
;     p0 = __builtin_amdgcn_mfma_f32_32x32x16_bf16(b0, qf, p0, 0, 0, 0);
;     p1 = __builtin_amdgcn_mfma_f32_32x32x16_bf16(b1, qf, p1, 0, 0, 0); }
; }
; __device__ __forceinline__ int v_st(int k, int c) { const int kk = (k & ~0xC) | ((k & 4) << 1) | ((k & 8) >> 1); return ((kk >> 3) * 4 + (c >> 5)) * 512 + ((kk & 7) * 32 + (c & 31)) * 2; }
; __device__ __forceinline__ int v_rd_base(int lane) { return ((lane & 3) << 3) | (((lane >> 2) & 3) << 6) | (((lane >> 4) & 1) << 5) | (((lane >> 5) & 1) << 8); }
; template <int OFF> __device__ __forceinline__ s16x4 tr_read(int vb) {
;   s16x4 r; asm volatile("ds_read_b64_tr_b16 %0, %1 offset:%2" : "=&v"(r) : "v"(vb), "i"(OFF) : "memory"); return r;
; }
; template <int D0> __device__ __forceinline__ void pv_one(f32x16& od, int vb, bf16x8 pa0, bf16x8 pa1, bf16x8 pa2, bf16x8 pa3) {
;   const s16x4 l0 = tr_read<v_rd_off(D0, 0, 0)>(vb), h0 = tr_read<v_rd_off(D0, 0, 1)>(vb), l1 = tr_read<v_rd_off(D0, 1, 0)>(vb), h1 = tr_read<v_rd_off(D0, 1, 1)>(vb);
;   const s16x4 l2 = tr_read<v_rd_off(D0, 2, 0)>(vb), h2 = tr_read<v_rd_off(D0, 2, 1)>(vb), l3 = tr_read<v_rd_off(D0, 3, 0)>(vb), h3 = tr_read<v_rd_off(D0, 3, 1)>(vb);
;   asm volatile("s_waitcnt lgkmcnt(0)" ::: "memory"); SBAR();
;     ...
;   od = __builtin_amdgcn_mfma_f32_32x32x16_bf16(pa0, PK(l0, h0), od, 0, 0, 0);
;   od = __builtin_amdgcn_mfma_f32_32x32x16_bf16(pa1, PK(l1, h1), od, 0, 0, 0);
;   od = __builtin_amdgcn_mfma_f32_32x32x16_bf16(pa2, PK(l2, h2), od, 0, 0, 0);
	v_mfma_f32_32x32x16_bf16 v[80:95], v[224:227], v[232:235], v[80:95]
	v_add_f32_e32 v225, v207, v210
	v_mov_b32_e32 v226, v225
	s_nop 1
	v_permlane32_swap_b32_e32 v225, v226
	v_cvt_pk_bf16_f32 v210, v143, v144
	v_cvt_pk_bf16_f32 v144, v135, v137
	v_cvt_pk_bf16_f32 v137, v156, v157
	s_waitcnt lgkmcnt(0)
	v_mfma_f32_32x32x16_bf16 v[64:79], v[228:231], v[232:235], v[64:79]
	v_cvt_pk_bf16_f32 v143, v221, v207
	v_permlane32_swap_b32_e32 v210, v212
	v_permlane32_swap_b32_e32 v144, v146
	v_permlane32_swap_b32_e32 v137, v139
	v_permlane32_swap_b32_e32 v141, v143
	ds_read_b64_tr_b16 v[240:241], v162 offset:0
	ds_read_b64_tr_b16 v[242:243], v162 offset:0x800
	ds_read_b64_tr_b16 v[244:245], v162 offset:0x1000
	ds_read_b64_tr_b16 v[246:247], v162 offset:0x1800
	ds_read_b64_tr_b16 v[248:249], v162 offset:0x2000
	ds_read_b64_tr_b16 v[250:251], v162 offset:0x2800
	ds_read_b64_tr_b16 v[148:149], v162 offset:0x3000
	ds_read_b64_tr_b16 v[150:151], v162 offset:0x3800
	s_waitcnt lgkmcnt(0)
	s_nop 0
	v_mfma_f32_32x32x16_bf16 v[48:63], v[210:213], v[240:243], v[48:63]
	ds_read_b64_tr_b16 v[240:241], v162 offset:0x200
	ds_read_b64_tr_b16 v[242:243], v162 offset:0xa00
	v_max_f32_e32 v164, v81, v81
	v_max_f32_e32 v165, v80, v80
	v_max_f32_e32 v164, v165, v164
	v_max3_f32 v164, v164, v82, v83
	v_max3_f32 v164, v164, v84, v85
	v_mfma_f32_32x32x16_bf16 v[48:63], v[144:147], v[244:247], v[48:63]
	ds_read_b64_tr_b16 v[244:245], v162 offset:0x1200
	ds_read_b64_tr_b16 v[246:247], v162 offset:0x1a00
	v_max3_f32 v164, v164, v86, v87
	v_max3_f32 v164, v164, v88, v89
	v_max3_f32 v164, v164, v90, v91
	v_max3_f32 v164, v164, v92, v93
	v_max3_f32 v164, v164, v94, v95
	v_mfma_f32_32x32x16_bf16 v[48:63], v[136:139], v[248:251], v[48:63]
	ds_read_b64_tr_b16 v[248:249], v162 offset:0x2200
	ds_read_b64_tr_b16 v[250:251], v162 offset:0x2a00
	ds_read_b64_tr_b16 v[156:157], v162 offset:0x3200
	ds_read_b64_tr_b16 v[158:159], v162 offset:0x3a00
	v_max3_f32 v164, v164, v64, v65
	v_max3_f32 v164, v164, v66, v67
	v_max3_f32 v164, v164, v68, v69
	v_max3_f32 v164, v164, v70, v71
	v_max3_f32 v164, v164, v72, v73
	s_waitcnt lgkmcnt(0)
	v_mfma_f32_32x32x16_bf16 v[48:63], v[140:143], v[148:151], v[48:63]
	v_max3_f32 v164, v164, v74, v75
	v_max3_f32 v164, v164, v76, v77
	v_max3_f32 v164, v164, v78, v79
	v_mfma_f32_32x32x16_bf16 v[32:47], v[210:213], v[240:243], v[32:47]
	ds_read_b64_tr_b16 v[148:149], v162 offset:0x400
	ds_read_b64_tr_b16 v[150:151], v162 offset:0xc00
	ds_read_b64_tr_b16 v[240:241], v162 offset:0x1400
	ds_read_b64_tr_b16 v[242:243], v162 offset:0x1c00
	v_mov_b32_e32 v165, v164
	s_nop 1
	v_permlane32_swap_b32_e32 v164, v165
	v_max_f32_e32 v165, v165, v165
	v_max_f32_e32 v164, v164, v164
	v_max_f32_e32 v164, v164, v165
	v_mfma_f32_32x32x16_bf16 v[32:47], v[144:147], v[244:247], v[32:47]
	ds_read_b64_tr_b16 v[244:245], v162 offset:0x2400
	ds_read_b64_tr_b16 v[246:247], v162 offset:0x2c00
	v_max_f32_e32 v166, v134, v134
	v_sub_f32_e32 v165, v164, v134
	v_max_f32_e32 v164, v166, v164
	v_sub_f32_e32 v166, v134, v164
	v_mul_f32_e32 v166, 0x3dd53b94, v166
	v_mfma_f32_32x32x16_bf16 v[32:47], v[136:139], v[248:251], v[32:47]
	ds_read_b64_tr_b16 v[248:249], v162 offset:0x3400
	ds_read_b64_tr_b16 v[250:251], v162 offset:0x3c00
	v_exp_f32_e32 v166, v166
	v_cmp_ge_f32_e32 vcc, s69, v165
	s_cmp_eq_u64 vcc, exec
	s_cselect_b64 s[8:9], -1, 0
	v_cndmask_b32_e64 v207, v166, 1.0, s[8:9]
	v_cndmask_b32_e64 v195, v164, v134, s[8:9]
	v_mul_f32_e32 v168, 0xbdd53b94, v195
	v_mov_b32_e32 v187, v168
	s_waitcnt lgkmcnt(0)
	v_mfma_f32_32x32x16_bf16 v[32:47], v[140:143], v[156:159], v[32:47]
	v_fmamk_f32 v80, v80, 0x3dd53b94, v168
	v_fmamk_f32 v81, v81, 0x3dd53b94, v168
	v_fmamk_f32 v82, v82, 0x3dd53b94, v168
	v_fmamk_f32 v83, v83, 0x3dd53b94, v168
	v_fmamk_f32 v84, v84, 0x3dd53b94, v168
	v_fmamk_f32 v85, v85, 0x3dd53b94, v168
	v_mfma_f32_32x32x16_bf16 v[16:31], v[210:213], v[148:151], v[16:31]
	ds_read_b64_tr_b16 v[148:149], v162 offset:0x600
	ds_read_b64_tr_b16 v[150:151], v162 offset:0xe00
	ds_read_b64_tr_b16 v[156:157], v162 offset:0x1600
	ds_read_b64_tr_b16 v[158:159], v162 offset:0x1e00
	v_fmamk_f32 v86, v86, 0x3dd53b94, v168
	v_fmamk_f32 v87, v87, 0x3dd53b94, v168
	v_fmamk_f32 v88, v88, 0x3dd53b94, v168
	v_fmamk_f32 v89, v89, 0x3dd53b94, v168
	v_fmamk_f32 v90, v90, 0x3dd53b94, v168
	v_fmamk_f32 v91, v91, 0x3dd53b94, v168
	v_mfma_f32_32x32x16_bf16 v[16:31], v[144:147], v[240:243], v[16:31]
	ds_read_b64_tr_b16 v[240:241], v162 offset:0x2600
	ds_read_b64_tr_b16 v[242:243], v162 offset:0x2e00
	v_fmamk_f32 v92, v92, 0x3dd53b94, v168
	v_fmamk_f32 v93, v93, 0x3dd53b94, v168
	v_fmamk_f32 v94, v94, 0x3dd53b94, v168
	v_fmac_f32_e32 v187, 0x3dd53b94, v95
	v_fmamk_f32 v134, v72, 0x3dd53b94, v168
	v_fmamk_f32 v135, v73, 0x3dd53b94, v168
	v_mfma_f32_32x32x16_bf16 v[16:31], v[136:139], v[244:247], v[16:31]
	ds_read_b64_tr_b16 v[244:245], v162 offset:0x3600
	ds_read_b64_tr_b16 v[246:247], v162 offset:0x3e00
	v_exp_f32_e32 v217, v81
	v_exp_f32_e32 v218, v82
	v_exp_f32_e32 v220, v83
	v_exp_f32_e32 v221, v84
	s_waitcnt lgkmcnt(0)
	v_mfma_f32_32x32x16_bf16 v[16:31], v[140:143], v[248:251], v[16:31]
	v_exp_f32_e32 v223, v85
	v_exp_f32_e32 v222, v86
	v_exp_f32_e32 v224, v87
	v_exp_f32_e32 v209, v88
	v_mfma_f32_32x32x16_bf16 v[0:15], v[210:213], v[148:151], v[0:15]
	v_fmamk_f32 v148, v74, 0x3dd53b94, v168
	v_fmamk_f32 v149, v75, 0x3dd53b94, v168
	v_exp_f32_e32 v214, v91
	v_exp_f32_e32 v215, v93
	v_exp_f32_e32 v216, v94
	v_mfma_f32_32x32x16_bf16 v[0:15], v[144:147], v[156:159], v[0:15]
	v_fmamk_f32 v146, v64, 0x3dd53b94, v168
	v_fmamk_f32 v147, v65, 0x3dd53b94, v168
	v_fmamk_f32 v144, v66, 0x3dd53b94, v168
	v_fmamk_f32 v145, v67, 0x3dd53b94, v168
	v_exp_f32_e32 v219, v187
	v_exp_f32_e32 v213, v80
	v_mfma_f32_32x32x16_bf16 v[0:15], v[136:139], v[240:243], v[0:15]
	v_fmamk_f32 v136, v70, 0x3dd53b94, v168
	v_fmamk_f32 v137, v71, 0x3dd53b94, v168
	v_fmamk_f32 v138, v78, 0x3dd53b94, v168
	v_fmamk_f32 v139, v79, 0x3dd53b94, v168
	v_exp_f32_e32 v210, v89
	v_exp_f32_e32 v211, v90
	v_add_f32_e32 v64, v205, v206
	v_fmac_f32_e32 v64, v188, v161
	v_add_f32_e32 v161, v225, v226
	v_fmac_f32_e32 v161, v64, v208
	v_mov_b32_e32 v188, v207
	v_mfma_f32_32x32x16_bf16 v[0:15], v[140:143], v[244:247], v[0:15]
	v_fmamk_f32 v140, v68, 0x3dd53b94, v168
	v_fmamk_f32 v141, v69, 0x3dd53b94, v168
	v_fmamk_f32 v142, v76, 0x3dd53b94, v168
	v_fmamk_f32 v143, v77, 0x3dd53b94, v168
	v_exp_f32_e32 v212, v92
	v_cmp_gt_f32_e32 vcc, 1.0, v207
	s_cbranch_vccz .LBB0_361
; #define SBAR() __builtin_amdgcn_sched_barrier(0)
; #define SLOAD(k0) do { s_v0 = *(const bf16x8*)(&Vh[(long)((k0) + sr) * LDK + sc]); s_v1 = *(const bf16x8*)(&Vh[(long)((k0) + 32 + sr) * LDK + sc]); \
;     s_k0 = *(const bf16x8*)(&Kh[(long)((k0) + sr) * LDK + sc]); s_k1 = *(const bf16x8*)(&Kh[(long)((k0) + 32 + sr) * LDK + sc]);                     \
;     s_r = *(const bf16x8*)(&Kr[(long)((k0) + rr_) * LDKR + rs_ * 8]); } while (0)
; #define SWRITE(b) do { *(bf16x8*)(V_lds + (b) * SHM_V + vst0) = s_v0; *(bf16x8*)(V_lds + (b) * SHM_V + vst1) = s_v1; const int kc = sc * 2; \
;     *(bf16x8*)(K_lds + (b) * SHM_K + KSWZ(sr, kc)) = s_k0; *(bf16x8*)(K_lds + (b) * SHM_K + KSWZ(32 + sr, kc)) = s_k1;                      \
;     *(bf16x8*)(R_lds + (b) * SHM_KR + RSWZ(rr_, rs_)) = s_r; } while (0)
; #define RESC(a) do { if (__any((a) < 1.f)) { if (hi == 0) al_l[r32] = (a); asm volatile("s_waitcnt lgkmcnt(0)" ::: "memory"); \
;     _Pragma("unroll") for (int d = 0; d < 4; ++d) _Pragma("unroll") for (int r = 0; r < 16; ++r) o[d][r] *= al_l[crow(r, hi)]; } } while (0)
; __device__ __forceinline__ void attn_item(const u16* __restrict__ Qb, const u16* __restrict__ Kh, const u16* __restrict__ Vh, const u16* __restrict__ Kr,
;                                           const u16* __restrict__ gaP, u16* mgP, int seq, char* lds) {
;     ...
;   for (int j = 1; j + 1 < NT; j += 2) {
;     SBAR(); qkt(pB0, pB1, K_lds + SHM_K, R_lds + SHM_KR, qr, Q_lds, r32, hi);
;     finishSM(pA0, pA1, alA, l_reg, pa0, pa1, pa2, pa3); SBAR();
;     SLOAD((j + 1) * 64); SBAR();
;     pv_d0(o, vb0, pa0, pa1, pa2, pa3); partialSM(pB0, pB1, m_reg, mnB, alB);
;     __syncthreads(); SWRITE(0);
;     RESC(alB); __syncthreads();
;     SBAR(); qkt(pA0, pA1, K_lds, R_lds, qr, Q_lds, r32, hi);
;     finishSM(pB0, pB1, alB, l_reg, pa0, pa1, pa2, pa3); SBAR();
;     SLOAD((j + 2) * 64); SBAR();
;     pv_d0(o, vb0 + SHM_V, pa0, pa1, pa2, pa3); partialSM(pA0, pA1, m_reg, mnA, alA);
;     __syncthreads(); SWRITE(1);
;     RESC(alA); __syncthreads();
;   }
	s_and_saveexec_b64 s[10:11], s[6:7]
	ds_write_b32 v160, v207 offset:128
	s_or_b64 exec, exec, s[10:11]
	s_waitcnt lgkmcnt(0)
	v_add_u32_e32 v150, v253, v128
	ds_read_b128 v[240:243], v150 offset:224
	ds_read_b128 v[244:247], v150 offset:192
	ds_read_b128 v[248:251], v150 offset:160
	ds_read_b128 v[156:159], v150 offset:128
	s_waitcnt lgkmcnt(3)
	v_pk_mul_f32 v[60:61], v[60:61], v[240:241]
	s_waitcnt lgkmcnt(2)
	v_pk_mul_f32 v[56:57], v[56:57], v[244:245]
	s_waitcnt lgkmcnt(1)
	v_pk_mul_f32 v[52:53], v[52:53], v[248:249]
	v_pk_mul_f32 v[62:63], v[62:63], v[242:243]
	v_pk_mul_f32 v[58:59], v[58:59], v[246:247]
	v_pk_mul_f32 v[54:55], v[54:55], v[250:251]
	s_waitcnt lgkmcnt(0)
	v_pk_mul_f32 v[50:51], v[50:51], v[158:159]
	v_pk_mul_f32 v[48:49], v[48:49], v[156:157]
	v_pk_mul_f32 v[44:45], v[44:45], v[240:241]
	v_pk_mul_f32 v[40:41], v[40:41], v[244:245]
	v_pk_mul_f32 v[36:37], v[36:37], v[248:249]
	v_pk_mul_f32 v[46:47], v[46:47], v[242:243]
	v_pk_mul_f32 v[42:43], v[42:43], v[246:247]
	v_pk_mul_f32 v[38:39], v[38:39], v[250:251]
	v_pk_mul_f32 v[34:35], v[34:35], v[158:159]
	v_pk_mul_f32 v[32:33], v[32:33], v[156:157]
	v_pk_mul_f32 v[28:29], v[28:29], v[240:241]
	v_pk_mul_f32 v[24:25], v[24:25], v[244:245]
	v_pk_mul_f32 v[20:21], v[20:21], v[248:249]
	v_pk_mul_f32 v[30:31], v[30:31], v[242:243]
	v_pk_mul_f32 v[26:27], v[26:27], v[246:247]
	v_pk_mul_f32 v[22:23], v[22:23], v[250:251]
	v_pk_mul_f32 v[18:19], v[18:19], v[158:159]
	v_pk_mul_f32 v[16:17], v[16:17], v[156:157]
	v_pk_mul_f32 v[12:13], v[12:13], v[240:241]
	v_pk_mul_f32 v[8:9], v[8:9], v[244:245]
	v_pk_mul_f32 v[4:5], v[4:5], v[248:249]
	v_pk_mul_f32 v[14:15], v[14:15], v[242:243]
	v_pk_mul_f32 v[10:11], v[10:11], v[246:247]
	v_pk_mul_f32 v[6:7], v[6:7], v[250:251]
	v_pk_mul_f32 v[2:3], v[2:3], v[158:159]
	v_pk_mul_f32 v[0:1], v[0:1], v[156:157]
.LBB0_361:
	s_add_i32 s78, s78, 2
	s_cmp_lt_u32 s78, s77
	s_waitcnt vmcnt(0)
	s_waitcnt lgkmcnt(0)
	s_barrier
	s_cbranch_scc1 .LBB0_353
